# attention unit order per CU changed to (15-s, s, 31-s, 16+s)
# baseline (speedup 1.0000x reference)
.LBB5_809:
	s_lshr_b32 s0, s89, 3
	s_mul_i32 s3, s0, s90
	s_add_i32 s3, s3, s78
	s_cmpk_lt_i32 s3, 0x100
	s_cselect_b64 s[0:1], -1, 0
	s_cmpk_gt_i32 s3, 0xff
	s_cbranch_scc1 .LBB5_817
	s_and_b32 s92, s3, 7
	s_bfe_u32 s24, s89, 0x20001
	s_lshl_b32 s99, s24, 2
	s_lshr_b32 s24, 0x2301, s99
	s_and_b32 s24, s24, 3
	s_nop 0
	s_nop 0
	s_nop 0
	s_nop 0
	s_nop 0
	s_nop 0
	s_nop 0
	s_nop 0
	s_nop 0
	s_nop 0
	s_nop 0
	s_nop 0
	s_cmp_lt_i32 s24, 1
	s_cbranch_scc1 .LBB5_816
	s_cmp_lg_u32 s24, 1
	s_mov_b64 s[4:5], -1
	s_cbranch_scc0 .LBB5_813
	s_or_b32 s4, s92, 16
	s_xor_b32 s5, s92, 31
	s_cmp_eq_u32 s24, 2
	s_cselect_b32 s17, s4, s5
	s_mov_b64 s[4:5], 0
